# P1 de-phasing delay 13.6 us (4 x s_sleep 127) instead of 10 us
# baseline (speedup 1.0000x reference)
.LBB0_107:
	v_writelane_b32 v254, s59, 20
	v_writelane_b32 v254, s60, 21
	s_nop 1
	v_writelane_b32 v254, s61, 22
	s_or_b64 exec, exec, s[0:1]
	s_add_u32 s56, s90, 0x5f6ea00
	s_addc_u32 s57, s91, 0
	s_add_u32 s40, s90, 0x3eeea00
	s_addc_u32 s41, s91, 0
	s_add_u32 s96, s90, 0x6faea00
	s_addc_u32 s97, s91, 0
	s_add_u32 s0, s90, 0x7feea00
	s_addc_u32 s1, s91, 0
	v_writelane_b32 v254, s0, 23
	v_mov_b32_e32 v12, v0
	s_waitcnt lgkmcnt(0)
	v_writelane_b32 v254, s1, 24
	s_add_u32 s0, s90, 0x902ea00
	s_addc_u32 s1, s91, 0
	v_writelane_b32 v254, s0, 25
	s_add_u32 s94, s90, 0x1e6ea00
	s_addc_u32 s95, s91, 0
	v_writelane_b32 v254, s1, 26
	s_barrier
	v_readlane_b32 s27, v254, 20
	s_bitcmp0_b32 s27, 3
	s_cbranch_scc1 .Lstg1_done
	s_sleep 127
	s_sleep 127
	s_sleep 127
	s_sleep 127
